# GEMM K-loops (A0 x2, out-proj RG-LRU, B0 in-proj, out-proj NSA li=0): LDS-DMA pieces in scalar-base form, constant strides folded into per-lane offsets
# baseline (speedup 1.0000x reference)
.LBB0_835:
	v_add_u32_e32 v246, 0x80000, v138
	v_add_u32_e32 v247, 0x80000, v144
	v_add_u32_e32 v248, 0x100000, v144
	v_add_u32_e32 v249, 0x180000, v144
	v_add_u32_e32 v250, 0x80000, v136
	v_add_u32_e32 v251, 0x100000, v136
	v_add_u32_e32 v222, 0x180000, v136
	v_add_u32_e32 v223, 0x80, v144
	v_add_u32_e32 v224, 0x80080, v144
	v_add_u32_e32 v225, 0x100080, v144
	v_add_u32_e32 v226, 0x180080, v144
	v_add_u32_e32 v227, 0x80, v136
	v_add_u32_e32 v228, 0x80080, v136
	s_ashr_i32 s79, s78, 31
	s_lshl_b64 s[36:37], s[78:79], 21
	s_add_u32 s80, s18, s36
	s_addc_u32 s81, s19, s37
	s_and_b64 s[36:37], s[4:5], exec
	s_cselect_b32 s37, s81, s71
	s_cselect_b32 s38, s80, s70
	s_ashr_i32 s69, s68, 31
	s_lshl_b64 s[46:47], s[68:69], 21
	s_add_u32 s84, s39, s46
	s_addc_u32 s85, s76, s47
	s_and_b64 s[46:47], s[4:5], exec
	s_cselect_b32 s69, s85, s73
	s_cselect_b32 s74, s84, s72
	s_add_u32 s70, s70, 0x100080
	s_addc_u32 s71, s71, 0
	s_add_u32 s75, s72, 0x100
	v_mov_b32_e32 v0, 0
	s_addc_u32 s79, s73, 0
	s_mov_b32 s92, -2
	v_mov_b32_e32 v1, v0
	v_mov_b32_e32 v2, v0
	v_mov_b32_e32 v3, v0
	v_mov_b32_e32 v4, v0
	v_mov_b32_e32 v5, v0
	v_mov_b32_e32 v6, v0
	v_mov_b32_e32 v7, v0
	v_mov_b32_e32 v16, v0
	v_mov_b32_e32 v17, v0
	v_mov_b32_e32 v18, v0
	v_mov_b32_e32 v19, v0
	v_mov_b32_e32 v20, v0
	v_mov_b32_e32 v21, v0
	v_mov_b32_e32 v22, v0
	v_mov_b32_e32 v23, v0
	v_mov_b32_e32 v32, v0
	v_mov_b32_e32 v33, v0
	v_mov_b32_e32 v34, v0
	v_mov_b32_e32 v35, v0
	v_mov_b32_e32 v36, v0
	v_mov_b32_e32 v37, v0
	v_mov_b32_e32 v38, v0
	v_mov_b32_e32 v39, v0
	v_mov_b32_e32 v48, v0
	v_mov_b32_e32 v49, v0
	v_mov_b32_e32 v50, v0
	v_mov_b32_e32 v51, v0
	v_mov_b32_e32 v52, v0
	v_mov_b32_e32 v53, v0
	v_mov_b32_e32 v54, v0
	v_mov_b32_e32 v55, v0
	v_mov_b32_e32 v8, v0
	v_mov_b32_e32 v9, v0
	v_mov_b32_e32 v10, v0
	v_mov_b32_e32 v11, v0
	v_mov_b32_e32 v12, v0
	v_mov_b32_e32 v13, v0
	v_mov_b32_e32 v14, v0
	v_mov_b32_e32 v15, v0
	v_mov_b32_e32 v24, v0
	v_mov_b32_e32 v25, v0
	v_mov_b32_e32 v26, v0
	v_mov_b32_e32 v27, v0
	v_mov_b32_e32 v28, v0
	v_mov_b32_e32 v29, v0
	v_mov_b32_e32 v30, v0
	v_mov_b32_e32 v31, v0
	v_mov_b32_e32 v40, v0
	v_mov_b32_e32 v41, v0
	v_mov_b32_e32 v42, v0
	v_mov_b32_e32 v43, v0
	v_mov_b32_e32 v44, v0
	v_mov_b32_e32 v45, v0
	v_mov_b32_e32 v46, v0
	v_mov_b32_e32 v47, v0
	v_mov_b32_e32 v56, v0
	v_mov_b32_e32 v57, v0
	v_mov_b32_e32 v58, v0
	v_mov_b32_e32 v59, v0
	v_mov_b32_e32 v60, v0
	v_mov_b32_e32 v61, v0
	v_mov_b32_e32 v62, v0
	v_mov_b32_e32 v63, v0
	v_mov_b32_e32 v64, v0
	v_mov_b32_e32 v65, v0
	v_mov_b32_e32 v66, v0
	v_mov_b32_e32 v67, v0
	v_mov_b32_e32 v68, v0
	v_mov_b32_e32 v69, v0
	v_mov_b32_e32 v70, v0
	v_mov_b32_e32 v71, v0
	v_mov_b32_e32 v80, v0
	v_mov_b32_e32 v81, v0
	v_mov_b32_e32 v82, v0
	v_mov_b32_e32 v83, v0
	v_mov_b32_e32 v84, v0
	v_mov_b32_e32 v85, v0
	v_mov_b32_e32 v86, v0
	v_mov_b32_e32 v87, v0
	v_mov_b32_e32 v96, v0
	v_mov_b32_e32 v97, v0
	v_mov_b32_e32 v98, v0
	v_mov_b32_e32 v99, v0
	v_mov_b32_e32 v100, v0
	v_mov_b32_e32 v101, v0
	v_mov_b32_e32 v102, v0
	v_mov_b32_e32 v103, v0
	v_mov_b32_e32 v112, v0
	v_mov_b32_e32 v113, v0
	v_mov_b32_e32 v114, v0
	v_mov_b32_e32 v115, v0
	v_mov_b32_e32 v116, v0
	v_mov_b32_e32 v117, v0
	v_mov_b32_e32 v118, v0
	v_mov_b32_e32 v119, v0
	v_mov_b32_e32 v72, v0
	v_mov_b32_e32 v73, v0
	v_mov_b32_e32 v74, v0
	v_mov_b32_e32 v75, v0
	v_mov_b32_e32 v76, v0
	v_mov_b32_e32 v77, v0
	v_mov_b32_e32 v78, v0
	v_mov_b32_e32 v79, v0
	v_mov_b32_e32 v88, v0
	v_mov_b32_e32 v89, v0
	v_mov_b32_e32 v90, v0
	v_mov_b32_e32 v91, v0
	v_mov_b32_e32 v92, v0
	v_mov_b32_e32 v93, v0
	v_mov_b32_e32 v94, v0
	v_mov_b32_e32 v95, v0
	v_mov_b32_e32 v104, v0
	v_mov_b32_e32 v105, v0
	v_mov_b32_e32 v106, v0
	v_mov_b32_e32 v107, v0
	v_mov_b32_e32 v108, v0
	v_mov_b32_e32 v109, v0
	v_mov_b32_e32 v110, v0
	v_mov_b32_e32 v111, v0
	v_mov_b32_e32 v120, v0
	v_mov_b32_e32 v121, v0
	v_mov_b32_e32 v122, v0
	v_mov_b32_e32 v123, v0
	v_mov_b32_e32 v124, v0
	v_mov_b32_e32 v125, v0
	v_mov_b32_e32 v126, v0
	v_mov_b32_e32 v127, v0
.LBB0_836:
	s_add_u32 s36, s70, 0xfff00080
	s_addc_u32 s44, s71, -1
	s_add_i32 s45, 0, 0x10000
	s_cmp_eq_u32 s92, 60
	s_cselect_b32 s73, s37, s44
	s_cselect_b32 s72, s38, s36
	s_cselect_b32 s47, s69, s79
	s_cselect_b32 s46, s74, s75
	s_add_i32 s36, 0, 0x14000
	v_add_u32_e32 v150, s45, v160
	v_add_u32_e32 v154, s36, v160
	ds_read_b128 v[128:131], v150
	ds_read_b128 v[132:135], v150 offset:1024
	ds_read_b128 v[140:143], v150 offset:2048
	ds_read_b128 v[150:153], v150 offset:3072
	ds_read_b128 v[156:159], v154
	ds_read_b128 v[164:167], v154 offset:1024
	ds_read_b128 v[174:177], v154 offset:2048
	ds_read_b128 v[180:183], v154 offset:3072
	s_add_i32 m0, s20, 0xc000
	ds_read_b128 v[184:187], v162
	ds_read_b128 v[188:191], v162 offset:1024
	ds_read_b128 v[192:195], v162 offset:2048
	ds_read_b128 v[196:199], v162 offset:3072
	ds_read_b128 v[204:207], v162 offset:4096
	ds_read_b128 v[208:211], v162 offset:5120
	ds_read_b128 v[212:215], v162 offset:6144
	ds_read_b128 v[216:219], v162 offset:7168
	global_load_lds_dwordx4 v138, s[70:71]
	s_add_i32 m0, s20, 0xe000
	s_nop 0
	global_load_lds_dwordx4 v246, s[70:71]
	s_waitcnt vmcnt(8)
	s_waitcnt lgkmcnt(0)
	s_barrier
	s_setprio 1
	s_waitcnt lgkmcnt(0)
	v_mfma_f32_16x16x32_bf16 v[124:127], v[128:131], v[184:187], v[124:127]
	v_mfma_f32_16x16x32_bf16 v[120:123], v[140:143], v[184:187], v[120:123]
	v_mfma_f32_16x16x32_bf16 v[108:111], v[128:131], v[192:195], v[108:111]
	v_mfma_f32_16x16x32_bf16 v[104:107], v[140:143], v[192:195], v[104:107]
	v_mfma_f32_16x16x32_bf16 v[92:95], v[128:131], v[204:207], v[92:95]
	v_mfma_f32_16x16x32_bf16 v[88:91], v[140:143], v[204:207], v[88:91]
	v_mfma_f32_16x16x32_bf16 v[76:79], v[128:131], v[212:215], v[76:79]
	v_mfma_f32_16x16x32_bf16 v[72:75], v[140:143], v[212:215], v[72:75]
	v_mfma_f32_16x16x32_bf16 v[124:127], v[132:135], v[188:191], v[124:127]
	v_mfma_f32_16x16x32_bf16 v[120:123], v[150:153], v[188:191], v[120:123]
	v_mfma_f32_16x16x32_bf16 v[108:111], v[132:135], v[196:199], v[108:111]
	v_mfma_f32_16x16x32_bf16 v[104:107], v[150:153], v[196:199], v[104:107]
	v_mfma_f32_16x16x32_bf16 v[92:95], v[132:135], v[208:211], v[92:95]
	v_mfma_f32_16x16x32_bf16 v[88:91], v[150:153], v[208:211], v[88:91]
	v_mfma_f32_16x16x32_bf16 v[76:79], v[132:135], v[216:219], v[76:79]
	v_mfma_f32_16x16x32_bf16 v[72:75], v[150:153], v[216:219], v[72:75]
	s_setprio 0
	s_setprio 1
	v_mfma_f32_16x16x32_bf16 v[116:119], v[156:159], v[184:187], v[116:119]
	v_mfma_f32_16x16x32_bf16 v[112:115], v[174:177], v[184:187], v[112:115]
	v_mfma_f32_16x16x32_bf16 v[100:103], v[156:159], v[192:195], v[100:103]
	v_mfma_f32_16x16x32_bf16 v[96:99], v[174:177], v[192:195], v[96:99]
	v_mfma_f32_16x16x32_bf16 v[84:87], v[156:159], v[204:207], v[84:87]
	v_mfma_f32_16x16x32_bf16 v[80:83], v[174:177], v[204:207], v[80:83]
	v_mfma_f32_16x16x32_bf16 v[68:71], v[156:159], v[212:215], v[68:71]
	v_mfma_f32_16x16x32_bf16 v[64:67], v[174:177], v[212:215], v[64:67]
	v_mfma_f32_16x16x32_bf16 v[116:119], v[164:167], v[188:191], v[116:119]
	v_mfma_f32_16x16x32_bf16 v[112:115], v[180:183], v[188:191], v[112:115]
	v_mfma_f32_16x16x32_bf16 v[100:103], v[164:167], v[196:199], v[100:103]
	v_mfma_f32_16x16x32_bf16 v[96:99], v[180:183], v[196:199], v[96:99]
	v_mfma_f32_16x16x32_bf16 v[84:87], v[164:167], v[208:211], v[84:87]
	v_mfma_f32_16x16x32_bf16 v[80:83], v[180:183], v[208:211], v[80:83]
	v_mfma_f32_16x16x32_bf16 v[68:71], v[164:167], v[216:219], v[68:71]
	v_mfma_f32_16x16x32_bf16 v[64:67], v[180:183], v[216:219], v[64:67]
	s_setprio 0
	s_barrier
	s_add_i32 s44, s45, s17
	s_mov_b32 m0, s44
	ds_read_b128 v[184:187], v162 offset:16384
	ds_read_b128 v[188:191], v162 offset:17408
	ds_read_b128 v[192:195], v162 offset:18432
	ds_read_b128 v[196:199], v162 offset:19456
	ds_read_b128 v[204:207], v162 offset:20480
	ds_read_b128 v[208:211], v162 offset:21504
	ds_read_b128 v[212:215], v162 offset:22528
	ds_read_b128 v[216:219], v162 offset:23552
	global_load_lds_dwordx4 v144, s[46:47]
	s_add_i32 m0, s44, 0x2000
	s_add_i32 s36, s36, s17
	global_load_lds_dwordx4 v247, s[46:47]
	s_mov_b32 m0, s36
	s_nop 0
	global_load_lds_dwordx4 v248, s[46:47]
	s_add_i32 m0, s36, 0x2000
	s_nop 0
	global_load_lds_dwordx4 v249, s[46:47]
	s_mov_b32 m0, s20
	s_nop 0
	global_load_lds_dwordx4 v136, s[72:73]
	s_mov_b32 m0, s21
	s_nop 0
	global_load_lds_dwordx4 v250, s[72:73]
	s_waitcnt vmcnt(8)
	s_waitcnt lgkmcnt(0)
	s_barrier
	s_setprio 1
	s_waitcnt lgkmcnt(0)
	v_mfma_f32_16x16x32_bf16 v[60:63], v[128:131], v[184:187], v[60:63]
	v_mfma_f32_16x16x32_bf16 v[56:59], v[140:143], v[184:187], v[56:59]
	v_mfma_f32_16x16x32_bf16 v[44:47], v[128:131], v[192:195], v[44:47]
	v_mfma_f32_16x16x32_bf16 v[40:43], v[140:143], v[192:195], v[40:43]
	v_mfma_f32_16x16x32_bf16 v[28:31], v[128:131], v[204:207], v[28:31]
	v_mfma_f32_16x16x32_bf16 v[24:27], v[140:143], v[204:207], v[24:27]
	v_mfma_f32_16x16x32_bf16 v[12:15], v[128:131], v[212:215], v[12:15]
	v_mfma_f32_16x16x32_bf16 v[8:11], v[140:143], v[212:215], v[8:11]
	v_mfma_f32_16x16x32_bf16 v[60:63], v[132:135], v[188:191], v[60:63]
	v_mfma_f32_16x16x32_bf16 v[56:59], v[150:153], v[188:191], v[56:59]
	v_mfma_f32_16x16x32_bf16 v[44:47], v[132:135], v[196:199], v[44:47]
	v_mfma_f32_16x16x32_bf16 v[40:43], v[150:153], v[196:199], v[40:43]
	v_mfma_f32_16x16x32_bf16 v[28:31], v[132:135], v[208:211], v[28:31]
	v_mfma_f32_16x16x32_bf16 v[24:27], v[150:153], v[208:211], v[24:27]
	v_mfma_f32_16x16x32_bf16 v[12:15], v[132:135], v[216:219], v[12:15]
	v_mfma_f32_16x16x32_bf16 v[8:11], v[150:153], v[216:219], v[8:11]
	s_setprio 0
	s_setprio 1
	v_mfma_f32_16x16x32_bf16 v[52:55], v[156:159], v[184:187], v[52:55]
	v_mfma_f32_16x16x32_bf16 v[48:51], v[174:177], v[184:187], v[48:51]
	v_mfma_f32_16x16x32_bf16 v[36:39], v[156:159], v[192:195], v[36:39]
	v_mfma_f32_16x16x32_bf16 v[32:35], v[174:177], v[192:195], v[32:35]
	v_mfma_f32_16x16x32_bf16 v[20:23], v[156:159], v[204:207], v[20:23]
	v_mfma_f32_16x16x32_bf16 v[16:19], v[174:177], v[204:207], v[16:19]
	v_mfma_f32_16x16x32_bf16 v[4:7], v[156:159], v[212:215], v[4:7]
	v_mfma_f32_16x16x32_bf16 v[0:3], v[174:177], v[212:215], v[0:3]
	v_mfma_f32_16x16x32_bf16 v[52:55], v[164:167], v[188:191], v[52:55]
	v_mfma_f32_16x16x32_bf16 v[48:51], v[180:183], v[188:191], v[48:51]
	v_mfma_f32_16x16x32_bf16 v[36:39], v[164:167], v[196:199], v[36:39]
	v_mfma_f32_16x16x32_bf16 v[32:35], v[180:183], v[196:199], v[32:35]
	v_mfma_f32_16x16x32_bf16 v[20:23], v[164:167], v[208:211], v[20:23]
	v_mfma_f32_16x16x32_bf16 v[16:19], v[180:183], v[208:211], v[16:19]
	v_mfma_f32_16x16x32_bf16 v[4:7], v[164:167], v[216:219], v[4:7]
	v_mfma_f32_16x16x32_bf16 v[0:3], v[180:183], v[216:219], v[0:3]
	s_setprio 0
	s_barrier
	s_add_i32 s36, 0, 0x18000
	s_add_i32 s44, 0, 0x1c000
	v_add_u32_e32 v150, s36, v160
	v_add_u32_e32 v163, s44, v160
	ds_read_b128 v[128:131], v150
	ds_read_b128 v[132:135], v150 offset:1024
	ds_read_b128 v[140:143], v150 offset:2048
	ds_read_b128 v[150:153], v150 offset:3072
	ds_read_b128 v[156:159], v163
	ds_read_b128 v[164:167], v163 offset:1024
	ds_read_b128 v[174:177], v163 offset:2048
	ds_read_b128 v[180:183], v163 offset:3072
	s_mov_b32 m0, s22
	ds_read_b128 v[184:187], v162 offset:32768
	ds_read_b128 v[188:191], v162 offset:33792
	ds_read_b128 v[192:195], v162 offset:34816
	ds_read_b128 v[196:199], v162 offset:35840
	ds_read_b128 v[204:207], v162 offset:36864
	ds_read_b128 v[208:211], v162 offset:37888
	ds_read_b128 v[212:215], v162 offset:38912
	ds_read_b128 v[216:219], v162 offset:39936
	global_load_lds_dwordx4 v251, s[72:73]
	s_mov_b32 m0, s23
	s_nop 0
	global_load_lds_dwordx4 v222, s[72:73]
	s_waitcnt vmcnt(8)
	s_waitcnt lgkmcnt(0)
	s_barrier
	s_setprio 1
	s_waitcnt lgkmcnt(0)
	v_mfma_f32_16x16x32_bf16 v[124:127], v[128:131], v[184:187], v[124:127]
	v_mfma_f32_16x16x32_bf16 v[120:123], v[140:143], v[184:187], v[120:123]
	v_mfma_f32_16x16x32_bf16 v[108:111], v[128:131], v[192:195], v[108:111]
	v_mfma_f32_16x16x32_bf16 v[104:107], v[140:143], v[192:195], v[104:107]
	v_mfma_f32_16x16x32_bf16 v[92:95], v[128:131], v[204:207], v[92:95]
	v_mfma_f32_16x16x32_bf16 v[88:91], v[140:143], v[204:207], v[88:91]
	v_mfma_f32_16x16x32_bf16 v[76:79], v[128:131], v[212:215], v[76:79]
	v_mfma_f32_16x16x32_bf16 v[72:75], v[140:143], v[212:215], v[72:75]
	v_mfma_f32_16x16x32_bf16 v[124:127], v[132:135], v[188:191], v[124:127]
	v_mfma_f32_16x16x32_bf16 v[120:123], v[150:153], v[188:191], v[120:123]
	v_mfma_f32_16x16x32_bf16 v[108:111], v[132:135], v[196:199], v[108:111]
	v_mfma_f32_16x16x32_bf16 v[104:107], v[150:153], v[196:199], v[104:107]
	v_mfma_f32_16x16x32_bf16 v[92:95], v[132:135], v[208:211], v[92:95]
	v_mfma_f32_16x16x32_bf16 v[88:91], v[150:153], v[208:211], v[88:91]
	v_mfma_f32_16x16x32_bf16 v[76:79], v[132:135], v[216:219], v[76:79]
	v_mfma_f32_16x16x32_bf16 v[72:75], v[150:153], v[216:219], v[72:75]
	s_setprio 0
	s_setprio 1
	v_mfma_f32_16x16x32_bf16 v[116:119], v[156:159], v[184:187], v[116:119]
	v_mfma_f32_16x16x32_bf16 v[112:115], v[174:177], v[184:187], v[112:115]
	v_mfma_f32_16x16x32_bf16 v[100:103], v[156:159], v[192:195], v[100:103]
	v_mfma_f32_16x16x32_bf16 v[96:99], v[174:177], v[192:195], v[96:99]
	v_mfma_f32_16x16x32_bf16 v[84:87], v[156:159], v[204:207], v[84:87]
	v_mfma_f32_16x16x32_bf16 v[80:83], v[174:177], v[204:207], v[80:83]
	v_mfma_f32_16x16x32_bf16 v[68:71], v[156:159], v[212:215], v[68:71]
	v_mfma_f32_16x16x32_bf16 v[64:67], v[174:177], v[212:215], v[64:67]
	v_mfma_f32_16x16x32_bf16 v[116:119], v[164:167], v[188:191], v[116:119]
	v_mfma_f32_16x16x32_bf16 v[112:115], v[180:183], v[188:191], v[112:115]
	v_mfma_f32_16x16x32_bf16 v[100:103], v[164:167], v[196:199], v[100:103]
	v_mfma_f32_16x16x32_bf16 v[96:99], v[180:183], v[196:199], v[96:99]
	v_mfma_f32_16x16x32_bf16 v[84:87], v[164:167], v[208:211], v[84:87]
	v_mfma_f32_16x16x32_bf16 v[80:83], v[180:183], v[208:211], v[80:83]
	v_mfma_f32_16x16x32_bf16 v[68:71], v[164:167], v[216:219], v[68:71]
	v_mfma_f32_16x16x32_bf16 v[64:67], v[180:183], v[216:219], v[64:67]
	s_setprio 0
	s_barrier
	s_add_i32 s36, s36, s17
	s_mov_b32 m0, s36
	ds_read_b128 v[184:187], v162 offset:49152
	ds_read_b128 v[188:191], v162 offset:50176
	ds_read_b128 v[192:195], v162 offset:51200
	ds_read_b128 v[196:199], v162 offset:52224
	ds_read_b128 v[204:207], v162 offset:53248
	ds_read_b128 v[208:211], v162 offset:54272
	ds_read_b128 v[212:215], v162 offset:55296
	ds_read_b128 v[216:219], v162 offset:56320
	global_load_lds_dwordx4 v223, s[46:47]
	s_add_i32 m0, s36, 0x2000
	s_add_i32 s36, s44, s17
	global_load_lds_dwordx4 v224, s[46:47]
	s_mov_b32 m0, s36
	s_nop 0
	global_load_lds_dwordx4 v225, s[46:47]
	s_add_i32 m0, s36, 0x2000
	s_nop 0
	global_load_lds_dwordx4 v226, s[46:47]
	s_mov_b32 m0, s89
	s_nop 0
	global_load_lds_dwordx4 v227, s[72:73]
	s_mov_b32 m0, s90
	s_nop 0
	global_load_lds_dwordx4 v228, s[72:73]
	s_waitcnt vmcnt(8)
	s_waitcnt lgkmcnt(0)
	s_barrier
	s_setprio 1
	s_waitcnt lgkmcnt(0)
	v_mfma_f32_16x16x32_bf16 v[60:63], v[128:131], v[184:187], v[60:63]
	v_mfma_f32_16x16x32_bf16 v[56:59], v[140:143], v[184:187], v[56:59]
	v_mfma_f32_16x16x32_bf16 v[44:47], v[128:131], v[192:195], v[44:47]
	v_mfma_f32_16x16x32_bf16 v[40:43], v[140:143], v[192:195], v[40:43]
	v_mfma_f32_16x16x32_bf16 v[28:31], v[128:131], v[204:207], v[28:31]
	v_mfma_f32_16x16x32_bf16 v[24:27], v[140:143], v[204:207], v[24:27]
	v_mfma_f32_16x16x32_bf16 v[12:15], v[128:131], v[212:215], v[12:15]
	v_mfma_f32_16x16x32_bf16 v[8:11], v[140:143], v[212:215], v[8:11]
	v_mfma_f32_16x16x32_bf16 v[60:63], v[132:135], v[188:191], v[60:63]
	v_mfma_f32_16x16x32_bf16 v[56:59], v[150:153], v[188:191], v[56:59]
	v_mfma_f32_16x16x32_bf16 v[44:47], v[132:135], v[196:199], v[44:47]
	v_mfma_f32_16x16x32_bf16 v[40:43], v[150:153], v[196:199], v[40:43]
	v_mfma_f32_16x16x32_bf16 v[28:31], v[132:135], v[208:211], v[28:31]
	v_mfma_f32_16x16x32_bf16 v[24:27], v[150:153], v[208:211], v[24:27]
	v_mfma_f32_16x16x32_bf16 v[12:15], v[132:135], v[216:219], v[12:15]
	v_mfma_f32_16x16x32_bf16 v[8:11], v[150:153], v[216:219], v[8:11]
	s_setprio 0
	s_setprio 1
	v_mfma_f32_16x16x32_bf16 v[52:55], v[156:159], v[184:187], v[52:55]
	v_mfma_f32_16x16x32_bf16 v[48:51], v[174:177], v[184:187], v[48:51]
	v_mfma_f32_16x16x32_bf16 v[36:39], v[156:159], v[192:195], v[36:39]
	v_mfma_f32_16x16x32_bf16 v[32:35], v[174:177], v[192:195], v[32:35]
	v_mfma_f32_16x16x32_bf16 v[20:23], v[156:159], v[204:207], v[20:23]
	v_mfma_f32_16x16x32_bf16 v[16:19], v[174:177], v[204:207], v[16:19]
	v_mfma_f32_16x16x32_bf16 v[4:7], v[156:159], v[212:215], v[4:7]
	v_mfma_f32_16x16x32_bf16 v[0:3], v[174:177], v[212:215], v[0:3]
	v_mfma_f32_16x16x32_bf16 v[52:55], v[164:167], v[188:191], v[52:55]
	v_mfma_f32_16x16x32_bf16 v[48:51], v[180:183], v[188:191], v[48:51]
	v_mfma_f32_16x16x32_bf16 v[36:39], v[164:167], v[196:199], v[36:39]
	v_mfma_f32_16x16x32_bf16 v[32:35], v[180:183], v[196:199], v[32:35]
	v_mfma_f32_16x16x32_bf16 v[20:23], v[164:167], v[208:211], v[20:23]
	v_mfma_f32_16x16x32_bf16 v[16:19], v[180:183], v[208:211], v[16:19]
	v_mfma_f32_16x16x32_bf16 v[4:7], v[164:167], v[216:219], v[4:7]
	v_mfma_f32_16x16x32_bf16 v[0:3], v[180:183], v[216:219], v[0:3]
	s_setprio 0
	s_barrier
	s_add_i32 s92, s92, 2
	s_add_u32 s70, s70, 0x100
	s_addc_u32 s71, s71, 0
	s_add_u32 s75, s75, 0x100
	s_addc_u32 s79, s79, 0
	s_cmp_gt_u32 s92, 61
	s_cbranch_scc0 .LBB0_836
	s_and_b64 vcc, exec, s[52:53]
	s_cbranch_vccz .LBB0_839
	s_barrier

.LBB0_1402:
	v_add_u32_e32 v246, 0x80000, v132
	v_add_u32_e32 v247, 0x80000, v0
	v_add_u32_e32 v248, 0x100000, v0
	v_add_u32_e32 v249, 0x180000, v0
	v_add_u32_e32 v250, 0x80000, v130
	v_add_u32_e32 v251, 0x100000, v130
	v_add_u32_e32 v226, 0x180000, v130
	v_add_u32_e32 v227, 0x80, v0
	v_add_u32_e32 v228, 0x80080, v0
	v_add_u32_e32 v229, 0x100080, v0
	v_add_u32_e32 v230, 0x180080, v0
	v_add_u32_e32 v231, 0x80, v130
	v_add_u32_e32 v232, 0x80080, v130
	v_lshl_add_u32 v244, s26, 8, v156
	v_readlane_b32 s100, v253, 49
	v_ashrrev_i32_e32 v245, 31, v244
	v_readlane_b32 s101, v253, 50
	s_nop 1
	v_lshl_add_u64 v[244:245], v[244:245], 2, s[100:101]
	global_load_dword v236, v[244:245], off
	global_load_dword v237, v[244:245], off offset:64
	global_load_dword v238, v[244:245], off offset:128
	global_load_dword v239, v[244:245], off offset:192
	global_load_dword v240, v[244:245], off offset:512
	global_load_dword v241, v[244:245], off offset:576
	global_load_dword v242, v[244:245], off offset:640
	global_load_dword v243, v[244:245], off offset:704
	s_ashr_i32 s15, s14, 31
	s_lshl_b64 s[16:17], s[14:15], 21
	s_add_u32 s16, s43, s16
	s_addc_u32 s17, s44, s17
	s_and_b64 s[18:19], s[2:3], exec
	s_cselect_b32 s5, s17, s37
	s_cselect_b32 s15, s16, s36
	s_ashr_i32 s13, s12, 31
	s_lshl_b64 s[18:19], s[12:13], 21
	s_add_u32 s18, s41, s18
	s_addc_u32 s19, s42, s19
	s_and_b64 s[58:59], s[2:3], exec
	s_cselect_b32 s13, s19, s39
	s_cselect_b32 s27, s18, s38
	s_add_u32 s36, s36, 0x100080
	s_addc_u32 s37, s37, 0
	s_add_u32 s58, s38, 0x100
	v_mov_b32_e32 v2, 0
	s_addc_u32 s59, s39, 0
	s_mov_b32 s60, -2
	v_mov_b32_e32 v3, v2
	v_mov_b32_e32 v4, v2
	v_mov_b32_e32 v5, v2
	v_mov_b32_e32 v6, v2
	v_mov_b32_e32 v7, v2
	v_mov_b32_e32 v8, v2
	v_mov_b32_e32 v9, v2
	v_mov_b32_e32 v18, v2
	v_mov_b32_e32 v19, v2
	v_mov_b32_e32 v20, v2
	v_mov_b32_e32 v21, v2
	v_mov_b32_e32 v22, v2
	v_mov_b32_e32 v23, v2
	v_mov_b32_e32 v24, v2
	v_mov_b32_e32 v25, v2
	v_mov_b32_e32 v34, v2
	v_mov_b32_e32 v35, v2
	v_mov_b32_e32 v36, v2
	v_mov_b32_e32 v37, v2
	v_mov_b32_e32 v38, v2
	v_mov_b32_e32 v39, v2
	v_mov_b32_e32 v40, v2
	v_mov_b32_e32 v41, v2
	v_mov_b32_e32 v50, v2
	v_mov_b32_e32 v51, v2
	v_mov_b32_e32 v52, v2
	v_mov_b32_e32 v53, v2
	v_mov_b32_e32 v54, v2
	v_mov_b32_e32 v55, v2
	v_mov_b32_e32 v56, v2
	v_mov_b32_e32 v57, v2
	v_mov_b32_e32 v10, v2
	v_mov_b32_e32 v11, v2
	v_mov_b32_e32 v12, v2
	v_mov_b32_e32 v13, v2
	v_mov_b32_e32 v14, v2
	v_mov_b32_e32 v15, v2
	v_mov_b32_e32 v16, v2
	v_mov_b32_e32 v17, v2
	v_mov_b32_e32 v26, v2
	v_mov_b32_e32 v27, v2
	v_mov_b32_e32 v28, v2
	v_mov_b32_e32 v29, v2
	v_mov_b32_e32 v30, v2
	v_mov_b32_e32 v31, v2
	v_mov_b32_e32 v32, v2
	v_mov_b32_e32 v33, v2
	v_mov_b32_e32 v42, v2
	v_mov_b32_e32 v43, v2
	v_mov_b32_e32 v44, v2
	v_mov_b32_e32 v45, v2
	v_mov_b32_e32 v46, v2
	v_mov_b32_e32 v47, v2
	v_mov_b32_e32 v48, v2
	v_mov_b32_e32 v49, v2
	v_mov_b32_e32 v58, v2
	v_mov_b32_e32 v59, v2
	v_mov_b32_e32 v60, v2
	v_mov_b32_e32 v61, v2
	v_mov_b32_e32 v62, v2
	v_mov_b32_e32 v63, v2
	v_mov_b32_e32 v64, v2
	v_mov_b32_e32 v65, v2
	v_mov_b32_e32 v66, v2
	v_mov_b32_e32 v67, v2
	v_mov_b32_e32 v68, v2
	v_mov_b32_e32 v69, v2
	v_mov_b32_e32 v70, v2
	v_mov_b32_e32 v71, v2
	v_mov_b32_e32 v72, v2
	v_mov_b32_e32 v73, v2
	v_mov_b32_e32 v82, v2
	v_mov_b32_e32 v83, v2
	v_mov_b32_e32 v84, v2
	v_mov_b32_e32 v85, v2
	v_mov_b32_e32 v86, v2
	v_mov_b32_e32 v87, v2
	v_mov_b32_e32 v88, v2
	v_mov_b32_e32 v89, v2
	v_mov_b32_e32 v98, v2
	v_mov_b32_e32 v99, v2
	v_mov_b32_e32 v100, v2
	v_mov_b32_e32 v101, v2
	v_mov_b32_e32 v102, v2
	v_mov_b32_e32 v103, v2
	v_mov_b32_e32 v104, v2
	v_mov_b32_e32 v105, v2
	v_mov_b32_e32 v114, v2
	v_mov_b32_e32 v115, v2
	v_mov_b32_e32 v116, v2
	v_mov_b32_e32 v117, v2
	v_mov_b32_e32 v118, v2
	v_mov_b32_e32 v119, v2
	v_mov_b32_e32 v120, v2
	v_mov_b32_e32 v121, v2
	v_mov_b32_e32 v74, v2
	v_mov_b32_e32 v75, v2
	v_mov_b32_e32 v76, v2
	v_mov_b32_e32 v77, v2
	v_mov_b32_e32 v78, v2
	v_mov_b32_e32 v79, v2
	v_mov_b32_e32 v80, v2
	v_mov_b32_e32 v81, v2
	v_mov_b32_e32 v90, v2
	v_mov_b32_e32 v91, v2
	v_mov_b32_e32 v92, v2
	v_mov_b32_e32 v93, v2
	v_mov_b32_e32 v94, v2
	v_mov_b32_e32 v95, v2
	v_mov_b32_e32 v96, v2
	v_mov_b32_e32 v97, v2
	v_mov_b32_e32 v106, v2
	v_mov_b32_e32 v107, v2
	v_mov_b32_e32 v108, v2
	v_mov_b32_e32 v109, v2
	v_mov_b32_e32 v110, v2
	v_mov_b32_e32 v111, v2
	v_mov_b32_e32 v112, v2
	v_mov_b32_e32 v113, v2
	v_mov_b32_e32 v122, v2
	v_mov_b32_e32 v123, v2
	v_mov_b32_e32 v124, v2
	v_mov_b32_e32 v125, v2
	v_mov_b32_e32 v126, v2
	v_mov_b32_e32 v127, v2
	v_mov_b32_e32 v128, v2
	v_mov_b32_e32 v129, v2
.LBB0_1403:
	s_add_u32 s38, s36, 0xfff00080
	s_addc_u32 s39, s37, -1
	s_add_i32 s61, 0, 0x10000
	s_cmp_eq_u32 s60, 60
	s_cselect_b32 s39, s5, s39
	s_cselect_b32 s38, s15, s38
	s_cselect_b32 s63, s13, s59
	s_cselect_b32 s62, s27, s58
	s_add_i32 s64, 0, 0x14000
	v_add_u32_e32 v146, s61, v157
	v_add_u32_e32 v154, s64, v157
	ds_read_b128 v[134:137], v146
	ds_read_b128 v[138:141], v146 offset:1024
	ds_read_b128 v[142:145], v146 offset:2048
	ds_read_b128 v[146:149], v146 offset:3072
	ds_read_b128 v[150:153], v154
	ds_read_b128 v[172:175], v154 offset:1024
	ds_read_b128 v[176:179], v154 offset:2048
	ds_read_b128 v[190:193], v154 offset:3072
	s_add_i32 m0, s45, 0xc000
	ds_read_b128 v[194:197], v160
	ds_read_b128 v[198:201], v160 offset:1024
	ds_read_b128 v[202:205], v160 offset:2048
	ds_read_b128 v[206:209], v160 offset:3072
	ds_read_b128 v[210:213], v160 offset:4096
	ds_read_b128 v[214:217], v160 offset:5120
	ds_read_b128 v[218:221], v160 offset:6144
	ds_read_b128 v[222:225], v160 offset:7168
	global_load_lds_dwordx4 v132, s[36:37]
	s_add_i32 m0, s45, 0xe000
	s_nop 0
	global_load_lds_dwordx4 v246, s[36:37]
	s_waitcnt vmcnt(8)
	s_waitcnt lgkmcnt(0)
	s_barrier
	s_setprio 1
	s_waitcnt lgkmcnt(0)
	v_mfma_f32_16x16x32_bf16 v[126:129], v[134:137], v[194:197], v[126:129]
	v_mfma_f32_16x16x32_bf16 v[122:125], v[142:145], v[194:197], v[122:125]
	v_mfma_f32_16x16x32_bf16 v[110:113], v[134:137], v[202:205], v[110:113]
	v_mfma_f32_16x16x32_bf16 v[106:109], v[142:145], v[202:205], v[106:109]
	v_mfma_f32_16x16x32_bf16 v[94:97], v[134:137], v[210:213], v[94:97]
	v_mfma_f32_16x16x32_bf16 v[90:93], v[142:145], v[210:213], v[90:93]
	v_mfma_f32_16x16x32_bf16 v[78:81], v[134:137], v[218:221], v[78:81]
	v_mfma_f32_16x16x32_bf16 v[74:77], v[142:145], v[218:221], v[74:77]
	v_mfma_f32_16x16x32_bf16 v[126:129], v[138:141], v[198:201], v[126:129]
	v_mfma_f32_16x16x32_bf16 v[122:125], v[146:149], v[198:201], v[122:125]
	v_mfma_f32_16x16x32_bf16 v[110:113], v[138:141], v[206:209], v[110:113]
	v_mfma_f32_16x16x32_bf16 v[106:109], v[146:149], v[206:209], v[106:109]
	v_mfma_f32_16x16x32_bf16 v[94:97], v[138:141], v[214:217], v[94:97]
	v_mfma_f32_16x16x32_bf16 v[90:93], v[146:149], v[214:217], v[90:93]
	v_mfma_f32_16x16x32_bf16 v[78:81], v[138:141], v[222:225], v[78:81]
	v_mfma_f32_16x16x32_bf16 v[74:77], v[146:149], v[222:225], v[74:77]
	s_setprio 0
	s_setprio 1
	v_mfma_f32_16x16x32_bf16 v[118:121], v[150:153], v[194:197], v[118:121]
	v_mfma_f32_16x16x32_bf16 v[114:117], v[176:179], v[194:197], v[114:117]
	v_mfma_f32_16x16x32_bf16 v[102:105], v[150:153], v[202:205], v[102:105]
	v_mfma_f32_16x16x32_bf16 v[98:101], v[176:179], v[202:205], v[98:101]
	v_mfma_f32_16x16x32_bf16 v[86:89], v[150:153], v[210:213], v[86:89]
	v_mfma_f32_16x16x32_bf16 v[82:85], v[176:179], v[210:213], v[82:85]
	v_mfma_f32_16x16x32_bf16 v[70:73], v[150:153], v[218:221], v[70:73]
	v_mfma_f32_16x16x32_bf16 v[66:69], v[176:179], v[218:221], v[66:69]
	v_mfma_f32_16x16x32_bf16 v[118:121], v[172:175], v[198:201], v[118:121]
	v_mfma_f32_16x16x32_bf16 v[114:117], v[190:193], v[198:201], v[114:117]
	v_mfma_f32_16x16x32_bf16 v[102:105], v[172:175], v[206:209], v[102:105]
	v_mfma_f32_16x16x32_bf16 v[98:101], v[190:193], v[206:209], v[98:101]
	v_mfma_f32_16x16x32_bf16 v[86:89], v[172:175], v[214:217], v[86:89]
	v_mfma_f32_16x16x32_bf16 v[82:85], v[190:193], v[214:217], v[82:85]
	v_mfma_f32_16x16x32_bf16 v[70:73], v[172:175], v[222:225], v[70:73]
	v_mfma_f32_16x16x32_bf16 v[66:69], v[190:193], v[222:225], v[66:69]
	s_setprio 0
	s_barrier
	s_add_i32 s61, s61, s20
	s_mov_b32 m0, s61
	ds_read_b128 v[194:197], v160 offset:16384
	ds_read_b128 v[198:201], v160 offset:17408
	ds_read_b128 v[202:205], v160 offset:18432
	ds_read_b128 v[206:209], v160 offset:19456
	ds_read_b128 v[210:213], v160 offset:20480
	ds_read_b128 v[214:217], v160 offset:21504
	ds_read_b128 v[218:221], v160 offset:22528
	ds_read_b128 v[222:225], v160 offset:23552
	global_load_lds_dwordx4 v0, s[62:63]
	s_add_i32 m0, s61, 0x2000
	s_add_i32 s61, s64, s20
	global_load_lds_dwordx4 v247, s[62:63]
	s_mov_b32 m0, s61
	s_nop 0
	global_load_lds_dwordx4 v248, s[62:63]
	s_add_i32 m0, s61, 0x2000
	s_nop 0
	global_load_lds_dwordx4 v249, s[62:63]
	s_mov_b64 s[100:101], s[38:39]
	s_mov_b32 m0, s45
	s_nop 0
	global_load_lds_dwordx4 v130, s[100:101]
	s_mov_b32 m0, s46
	s_nop 0
	global_load_lds_dwordx4 v250, s[100:101]
	s_waitcnt vmcnt(8)
	s_waitcnt lgkmcnt(0)
	s_barrier
	s_setprio 1
	s_waitcnt lgkmcnt(0)
	v_mfma_f32_16x16x32_bf16 v[62:65], v[134:137], v[194:197], v[62:65]
	v_mfma_f32_16x16x32_bf16 v[58:61], v[142:145], v[194:197], v[58:61]
	v_mfma_f32_16x16x32_bf16 v[46:49], v[134:137], v[202:205], v[46:49]
	v_mfma_f32_16x16x32_bf16 v[42:45], v[142:145], v[202:205], v[42:45]
	v_mfma_f32_16x16x32_bf16 v[30:33], v[134:137], v[210:213], v[30:33]
	v_mfma_f32_16x16x32_bf16 v[26:29], v[142:145], v[210:213], v[26:29]
	v_mfma_f32_16x16x32_bf16 v[14:17], v[134:137], v[218:221], v[14:17]
	v_mfma_f32_16x16x32_bf16 v[10:13], v[142:145], v[218:221], v[10:13]
	v_mfma_f32_16x16x32_bf16 v[62:65], v[138:141], v[198:201], v[62:65]
	v_mfma_f32_16x16x32_bf16 v[58:61], v[146:149], v[198:201], v[58:61]
	v_mfma_f32_16x16x32_bf16 v[46:49], v[138:141], v[206:209], v[46:49]
	v_mfma_f32_16x16x32_bf16 v[42:45], v[146:149], v[206:209], v[42:45]
	v_mfma_f32_16x16x32_bf16 v[30:33], v[138:141], v[214:217], v[30:33]
	v_mfma_f32_16x16x32_bf16 v[26:29], v[146:149], v[214:217], v[26:29]
	v_mfma_f32_16x16x32_bf16 v[14:17], v[138:141], v[222:225], v[14:17]
	v_mfma_f32_16x16x32_bf16 v[10:13], v[146:149], v[222:225], v[10:13]
	s_setprio 0
	s_setprio 1
	v_mfma_f32_16x16x32_bf16 v[54:57], v[150:153], v[194:197], v[54:57]
	v_mfma_f32_16x16x32_bf16 v[50:53], v[176:179], v[194:197], v[50:53]
	v_mfma_f32_16x16x32_bf16 v[38:41], v[150:153], v[202:205], v[38:41]
	v_mfma_f32_16x16x32_bf16 v[34:37], v[176:179], v[202:205], v[34:37]
	v_mfma_f32_16x16x32_bf16 v[22:25], v[150:153], v[210:213], v[22:25]
	v_mfma_f32_16x16x32_bf16 v[18:21], v[176:179], v[210:213], v[18:21]
	v_mfma_f32_16x16x32_bf16 v[6:9], v[150:153], v[218:221], v[6:9]
	v_mfma_f32_16x16x32_bf16 v[2:5], v[176:179], v[218:221], v[2:5]
	v_mfma_f32_16x16x32_bf16 v[54:57], v[172:175], v[198:201], v[54:57]
	v_mfma_f32_16x16x32_bf16 v[50:53], v[190:193], v[198:201], v[50:53]
	v_mfma_f32_16x16x32_bf16 v[38:41], v[172:175], v[206:209], v[38:41]
	v_mfma_f32_16x16x32_bf16 v[34:37], v[190:193], v[206:209], v[34:37]
	v_mfma_f32_16x16x32_bf16 v[22:25], v[172:175], v[214:217], v[22:25]
	v_mfma_f32_16x16x32_bf16 v[18:21], v[190:193], v[214:217], v[18:21]
	v_mfma_f32_16x16x32_bf16 v[6:9], v[172:175], v[222:225], v[6:9]
	v_mfma_f32_16x16x32_bf16 v[2:5], v[190:193], v[222:225], v[2:5]
	s_setprio 0
	s_barrier
	s_add_i32 s38, 0, 0x18000
	s_add_i32 s39, 0, 0x1c000
	v_add_u32_e32 v146, s38, v157
	v_add_u32_e32 v159, s39, v157
	ds_read_b128 v[134:137], v146
	ds_read_b128 v[138:141], v146 offset:1024
	ds_read_b128 v[142:145], v146 offset:2048
	ds_read_b128 v[146:149], v146 offset:3072
	ds_read_b128 v[150:153], v159
	ds_read_b128 v[172:175], v159 offset:1024
	ds_read_b128 v[176:179], v159 offset:2048
	ds_read_b128 v[190:193], v159 offset:3072
	s_mov_b32 m0, s47
	ds_read_b128 v[194:197], v160 offset:32768
	ds_read_b128 v[198:201], v160 offset:33792
	ds_read_b128 v[202:205], v160 offset:34816
	ds_read_b128 v[206:209], v160 offset:35840
	ds_read_b128 v[210:213], v160 offset:36864
	ds_read_b128 v[214:217], v160 offset:37888
	ds_read_b128 v[218:221], v160 offset:38912
	ds_read_b128 v[222:225], v160 offset:39936
	global_load_lds_dwordx4 v251, s[100:101]
	s_mov_b32 m0, s52
	s_nop 0
	global_load_lds_dwordx4 v226, s[100:101]
	s_waitcnt vmcnt(8)
	s_waitcnt lgkmcnt(0)
	s_barrier
	s_setprio 1
	s_waitcnt lgkmcnt(0)
	v_mfma_f32_16x16x32_bf16 v[126:129], v[134:137], v[194:197], v[126:129]
	v_mfma_f32_16x16x32_bf16 v[122:125], v[142:145], v[194:197], v[122:125]
	v_mfma_f32_16x16x32_bf16 v[110:113], v[134:137], v[202:205], v[110:113]
	v_mfma_f32_16x16x32_bf16 v[106:109], v[142:145], v[202:205], v[106:109]
	v_mfma_f32_16x16x32_bf16 v[94:97], v[134:137], v[210:213], v[94:97]
	v_mfma_f32_16x16x32_bf16 v[90:93], v[142:145], v[210:213], v[90:93]
	v_mfma_f32_16x16x32_bf16 v[78:81], v[134:137], v[218:221], v[78:81]
	v_mfma_f32_16x16x32_bf16 v[74:77], v[142:145], v[218:221], v[74:77]
	v_mfma_f32_16x16x32_bf16 v[126:129], v[138:141], v[198:201], v[126:129]
	v_mfma_f32_16x16x32_bf16 v[122:125], v[146:149], v[198:201], v[122:125]
	v_mfma_f32_16x16x32_bf16 v[110:113], v[138:141], v[206:209], v[110:113]
	v_mfma_f32_16x16x32_bf16 v[106:109], v[146:149], v[206:209], v[106:109]
	v_mfma_f32_16x16x32_bf16 v[94:97], v[138:141], v[214:217], v[94:97]
	v_mfma_f32_16x16x32_bf16 v[90:93], v[146:149], v[214:217], v[90:93]
	v_mfma_f32_16x16x32_bf16 v[78:81], v[138:141], v[222:225], v[78:81]
	v_mfma_f32_16x16x32_bf16 v[74:77], v[146:149], v[222:225], v[74:77]
	s_setprio 0
	s_setprio 1
	v_mfma_f32_16x16x32_bf16 v[118:121], v[150:153], v[194:197], v[118:121]
	v_mfma_f32_16x16x32_bf16 v[114:117], v[176:179], v[194:197], v[114:117]
	v_mfma_f32_16x16x32_bf16 v[102:105], v[150:153], v[202:205], v[102:105]
	v_mfma_f32_16x16x32_bf16 v[98:101], v[176:179], v[202:205], v[98:101]
	v_mfma_f32_16x16x32_bf16 v[86:89], v[150:153], v[210:213], v[86:89]
	v_mfma_f32_16x16x32_bf16 v[82:85], v[176:179], v[210:213], v[82:85]
	v_mfma_f32_16x16x32_bf16 v[70:73], v[150:153], v[218:221], v[70:73]
	v_mfma_f32_16x16x32_bf16 v[66:69], v[176:179], v[218:221], v[66:69]
	v_mfma_f32_16x16x32_bf16 v[118:121], v[172:175], v[198:201], v[118:121]
	v_mfma_f32_16x16x32_bf16 v[114:117], v[190:193], v[198:201], v[114:117]
	v_mfma_f32_16x16x32_bf16 v[102:105], v[172:175], v[206:209], v[102:105]
	v_mfma_f32_16x16x32_bf16 v[98:101], v[190:193], v[206:209], v[98:101]
	v_mfma_f32_16x16x32_bf16 v[86:89], v[172:175], v[214:217], v[86:89]
	v_mfma_f32_16x16x32_bf16 v[82:85], v[190:193], v[214:217], v[82:85]
	v_mfma_f32_16x16x32_bf16 v[70:73], v[172:175], v[222:225], v[70:73]
	v_mfma_f32_16x16x32_bf16 v[66:69], v[190:193], v[222:225], v[66:69]
	s_setprio 0
	s_barrier
	s_add_i32 s38, s38, s20
	s_mov_b32 m0, s38
	ds_read_b128 v[194:197], v160 offset:49152
	ds_read_b128 v[198:201], v160 offset:50176
	ds_read_b128 v[202:205], v160 offset:51200
	ds_read_b128 v[206:209], v160 offset:52224
	ds_read_b128 v[210:213], v160 offset:53248
	ds_read_b128 v[214:217], v160 offset:54272
	ds_read_b128 v[218:221], v160 offset:55296
	ds_read_b128 v[222:225], v160 offset:56320
	global_load_lds_dwordx4 v227, s[62:63]
	s_add_i32 m0, s38, 0x2000
	s_add_i32 s38, s39, s20
	global_load_lds_dwordx4 v228, s[62:63]
	s_mov_b32 m0, s38
	s_nop 0
	global_load_lds_dwordx4 v229, s[62:63]
	s_add_i32 m0, s38, 0x2000
	s_nop 0
	global_load_lds_dwordx4 v230, s[62:63]
	s_mov_b32 m0, s53
	s_nop 0
	global_load_lds_dwordx4 v231, s[100:101]
	s_mov_b32 m0, s54
	s_nop 0
	global_load_lds_dwordx4 v232, s[100:101]
	s_waitcnt vmcnt(8)
	s_waitcnt lgkmcnt(0)
	s_barrier
	s_setprio 1
	s_waitcnt lgkmcnt(0)
	v_mfma_f32_16x16x32_bf16 v[62:65], v[134:137], v[194:197], v[62:65]
	v_mfma_f32_16x16x32_bf16 v[58:61], v[142:145], v[194:197], v[58:61]
	v_mfma_f32_16x16x32_bf16 v[46:49], v[134:137], v[202:205], v[46:49]
	v_mfma_f32_16x16x32_bf16 v[42:45], v[142:145], v[202:205], v[42:45]
	v_mfma_f32_16x16x32_bf16 v[30:33], v[134:137], v[210:213], v[30:33]
	v_mfma_f32_16x16x32_bf16 v[26:29], v[142:145], v[210:213], v[26:29]
	v_mfma_f32_16x16x32_bf16 v[14:17], v[134:137], v[218:221], v[14:17]
	v_mfma_f32_16x16x32_bf16 v[10:13], v[142:145], v[218:221], v[10:13]
	v_mfma_f32_16x16x32_bf16 v[62:65], v[138:141], v[198:201], v[62:65]
	v_mfma_f32_16x16x32_bf16 v[58:61], v[146:149], v[198:201], v[58:61]
	v_mfma_f32_16x16x32_bf16 v[46:49], v[138:141], v[206:209], v[46:49]
	v_mfma_f32_16x16x32_bf16 v[42:45], v[146:149], v[206:209], v[42:45]
	v_mfma_f32_16x16x32_bf16 v[30:33], v[138:141], v[214:217], v[30:33]
	v_mfma_f32_16x16x32_bf16 v[26:29], v[146:149], v[214:217], v[26:29]
	v_mfma_f32_16x16x32_bf16 v[14:17], v[138:141], v[222:225], v[14:17]
	v_mfma_f32_16x16x32_bf16 v[10:13], v[146:149], v[222:225], v[10:13]
	s_setprio 0
	s_setprio 1
	v_mfma_f32_16x16x32_bf16 v[54:57], v[150:153], v[194:197], v[54:57]
	v_mfma_f32_16x16x32_bf16 v[50:53], v[176:179], v[194:197], v[50:53]
	v_mfma_f32_16x16x32_bf16 v[38:41], v[150:153], v[202:205], v[38:41]
	v_mfma_f32_16x16x32_bf16 v[34:37], v[176:179], v[202:205], v[34:37]
	v_mfma_f32_16x16x32_bf16 v[22:25], v[150:153], v[210:213], v[22:25]
	v_mfma_f32_16x16x32_bf16 v[18:21], v[176:179], v[210:213], v[18:21]
	v_mfma_f32_16x16x32_bf16 v[6:9], v[150:153], v[218:221], v[6:9]
	v_mfma_f32_16x16x32_bf16 v[2:5], v[176:179], v[218:221], v[2:5]
	v_mfma_f32_16x16x32_bf16 v[54:57], v[172:175], v[198:201], v[54:57]
	v_mfma_f32_16x16x32_bf16 v[50:53], v[190:193], v[198:201], v[50:53]
	v_mfma_f32_16x16x32_bf16 v[38:41], v[172:175], v[206:209], v[38:41]
	v_mfma_f32_16x16x32_bf16 v[34:37], v[190:193], v[206:209], v[34:37]
	v_mfma_f32_16x16x32_bf16 v[22:25], v[172:175], v[214:217], v[22:25]
	v_mfma_f32_16x16x32_bf16 v[18:21], v[190:193], v[214:217], v[18:21]
	v_mfma_f32_16x16x32_bf16 v[6:9], v[172:175], v[222:225], v[6:9]
	v_mfma_f32_16x16x32_bf16 v[2:5], v[190:193], v[222:225], v[2:5]
	s_setprio 0
	s_barrier
	s_add_i32 s60, s60, 2
	s_add_u32 s36, s36, 0x100
	s_addc_u32 s37, s37, 0
	s_add_u32 s58, s58, 0x100
	s_addc_u32 s59, s59, 0
	s_cmp_gt_u32 s60, 61
	s_cbranch_scc0 .LBB0_1403
	s_and_b64 vcc, exec, s[10:11]
	s_cbranch_vccz .LBB0_1406
	s_barrier

.LBB0_3116:
	v_add_u32_e32 v246, 0x80000, v142
	v_add_u32_e32 v247, 0x80000, v140
	v_add_u32_e32 v248, 0x100000, v140
	v_add_u32_e32 v249, 0x180000, v140
	v_add_u32_e32 v250, 0x80000, v138
	v_add_u32_e32 v251, 0x100000, v138
	v_add_u32_e32 v232, 0x180000, v138
	v_add_u32_e32 v233, 0x80, v140
	v_add_u32_e32 v234, 0x80080, v140
	v_add_u32_e32 v235, 0x100080, v140
	v_add_u32_e32 v236, 0x180080, v140
	v_add_u32_e32 v237, 0x80, v138
	v_add_u32_e32 v238, 0x80080, v138
	s_ashr_i32 s17, s16, 31
	s_lshl_b64 s[18:19], s[16:17], 21
	s_add_u32 s18, s20, s18
	s_addc_u32 s19, s53, s19
	s_and_b64 s[26:27], s[4:5], exec
	s_cselect_b32 s17, s19, s39
	s_cselect_b32 s64, s18, s38
	s_ashr_i32 s15, s14, 31
	s_lshl_b64 s[26:27], s[14:15], 21
	s_add_u32 s26, s47, s26
	s_addc_u32 s27, s52, s27
	s_and_b64 s[66:67], s[4:5], exec
	s_cselect_b32 s15, s27, s41
	s_cselect_b32 s65, s26, s40
	s_add_u32 s38, s38, 0x100080
	s_addc_u32 s39, s39, 0
	s_add_u32 s66, s40, 0x100
	v_mov_b32_e32 v2, 0
	s_addc_u32 s67, s41, 0
	s_mov_b32 s68, -2
	v_mov_b32_e32 v3, v2
	v_mov_b32_e32 v4, v2
	v_mov_b32_e32 v5, v2
	v_mov_b32_e32 v6, v2
	v_mov_b32_e32 v7, v2
	v_mov_b32_e32 v8, v2
	v_mov_b32_e32 v9, v2
	v_mov_b32_e32 v18, v2
	v_mov_b32_e32 v19, v2
	v_mov_b32_e32 v20, v2
	v_mov_b32_e32 v21, v2
	v_mov_b32_e32 v22, v2
	v_mov_b32_e32 v23, v2
	v_mov_b32_e32 v24, v2
	v_mov_b32_e32 v25, v2
	v_mov_b32_e32 v34, v2
	v_mov_b32_e32 v35, v2
	v_mov_b32_e32 v36, v2
	v_mov_b32_e32 v37, v2
	v_mov_b32_e32 v38, v2
	v_mov_b32_e32 v39, v2
	v_mov_b32_e32 v40, v2
	v_mov_b32_e32 v41, v2
	v_mov_b32_e32 v50, v2
	v_mov_b32_e32 v51, v2
	v_mov_b32_e32 v52, v2
	v_mov_b32_e32 v53, v2
	v_mov_b32_e32 v54, v2
	v_mov_b32_e32 v55, v2
	v_mov_b32_e32 v56, v2
	v_mov_b32_e32 v57, v2
	v_mov_b32_e32 v10, v2
	v_mov_b32_e32 v11, v2
	v_mov_b32_e32 v12, v2
	v_mov_b32_e32 v13, v2
	v_mov_b32_e32 v14, v2
	v_mov_b32_e32 v15, v2
	v_mov_b32_e32 v16, v2
	v_mov_b32_e32 v17, v2
	v_mov_b32_e32 v26, v2
	v_mov_b32_e32 v27, v2
	v_mov_b32_e32 v28, v2
	v_mov_b32_e32 v29, v2
	v_mov_b32_e32 v30, v2
	v_mov_b32_e32 v31, v2
	v_mov_b32_e32 v32, v2
	v_mov_b32_e32 v33, v2
	v_mov_b32_e32 v42, v2
	v_mov_b32_e32 v43, v2
	v_mov_b32_e32 v44, v2
	v_mov_b32_e32 v45, v2
	v_mov_b32_e32 v46, v2
	v_mov_b32_e32 v47, v2
	v_mov_b32_e32 v48, v2
	v_mov_b32_e32 v49, v2
	v_mov_b32_e32 v58, v2
	v_mov_b32_e32 v59, v2
	v_mov_b32_e32 v60, v2
	v_mov_b32_e32 v61, v2
	v_mov_b32_e32 v62, v2
	v_mov_b32_e32 v63, v2
	v_mov_b32_e32 v64, v2
	v_mov_b32_e32 v65, v2
	v_mov_b32_e32 v66, v2
	v_mov_b32_e32 v67, v2
	v_mov_b32_e32 v68, v2
	v_mov_b32_e32 v69, v2
	v_mov_b32_e32 v70, v2
	v_mov_b32_e32 v71, v2
	v_mov_b32_e32 v72, v2
	v_mov_b32_e32 v73, v2
	v_mov_b32_e32 v82, v2
	v_mov_b32_e32 v83, v2
	v_mov_b32_e32 v84, v2
	v_mov_b32_e32 v85, v2
	v_mov_b32_e32 v86, v2
	v_mov_b32_e32 v87, v2
	v_mov_b32_e32 v88, v2
	v_mov_b32_e32 v89, v2
	v_mov_b32_e32 v98, v2
	v_mov_b32_e32 v99, v2
	v_mov_b32_e32 v100, v2
	v_mov_b32_e32 v101, v2
	v_mov_b32_e32 v102, v2
	v_mov_b32_e32 v103, v2
	v_mov_b32_e32 v104, v2
	v_mov_b32_e32 v105, v2
	v_mov_b32_e32 v114, v2
	v_mov_b32_e32 v115, v2
	v_mov_b32_e32 v116, v2
	v_mov_b32_e32 v117, v2
	v_mov_b32_e32 v118, v2
	v_mov_b32_e32 v119, v2
	v_mov_b32_e32 v120, v2
	v_mov_b32_e32 v121, v2
	v_mov_b32_e32 v74, v2
	v_mov_b32_e32 v75, v2
	v_mov_b32_e32 v76, v2
	v_mov_b32_e32 v77, v2
	v_mov_b32_e32 v78, v2
	v_mov_b32_e32 v79, v2
	v_mov_b32_e32 v80, v2
	v_mov_b32_e32 v81, v2
	v_mov_b32_e32 v90, v2
	v_mov_b32_e32 v91, v2
	v_mov_b32_e32 v92, v2
	v_mov_b32_e32 v93, v2
	v_mov_b32_e32 v94, v2
	v_mov_b32_e32 v95, v2
	v_mov_b32_e32 v96, v2
	v_mov_b32_e32 v97, v2
	v_mov_b32_e32 v106, v2
	v_mov_b32_e32 v107, v2
	v_mov_b32_e32 v108, v2
	v_mov_b32_e32 v109, v2
	v_mov_b32_e32 v110, v2
	v_mov_b32_e32 v111, v2
	v_mov_b32_e32 v112, v2
	v_mov_b32_e32 v113, v2
	v_mov_b32_e32 v122, v2
	v_mov_b32_e32 v123, v2
	v_mov_b32_e32 v124, v2
	v_mov_b32_e32 v125, v2
	v_mov_b32_e32 v126, v2
	v_mov_b32_e32 v127, v2
	v_mov_b32_e32 v128, v2
	v_mov_b32_e32 v129, v2
.LBB0_3117:
	s_add_u32 s40, s38, 0xfff00080
	s_addc_u32 s41, s39, -1
	s_add_i32 s69, 0, 0x10000
	s_cmp_eq_u32 s68, 60
	s_cselect_b32 s41, s17, s41
	s_cselect_b32 s40, s64, s40
	v_add_u32_e32 v145, s69, v155
	s_cselect_b32 s71, s15, s67
	s_cselect_b32 s70, s65, s66
	s_add_i32 s72, 0, 0x14000
	ds_read_b128 v[130:133], v145
	ds_read_b128 v[134:137], v145 offset:1024
	ds_read_b128 v[148:151], v145 offset:2048
	ds_read_b128 v[164:167], v145 offset:3072
	v_add_u32_e32 v145, s72, v155
	ds_read_b128 v[172:175], v145
	ds_read_b128 v[176:179], v145 offset:1024
	ds_read_b128 v[190:193], v145 offset:2048
	ds_read_b128 v[194:197], v145 offset:3072
	s_add_i32 m0, s54, 0xc000
	ds_read_b128 v[198:201], v157
	ds_read_b128 v[202:205], v157 offset:1024
	ds_read_b128 v[206:209], v157 offset:2048
	ds_read_b128 v[210:213], v157 offset:3072
	ds_read_b128 v[214:217], v157 offset:4096
	ds_read_b128 v[218:221], v157 offset:5120
	ds_read_b128 v[222:225], v157 offset:6144
	ds_read_b128 v[226:229], v157 offset:7168
	global_load_lds_dwordx4 v142, s[38:39]
	s_add_i32 m0, s54, 0xe000
	s_nop 0
	global_load_lds_dwordx4 v246, s[38:39]
	s_waitcnt vmcnt(8)
	s_waitcnt lgkmcnt(0)
	s_barrier
	s_setprio 1
	s_waitcnt lgkmcnt(0)
	v_mfma_f32_16x16x32_bf16 v[126:129], v[130:133], v[198:201], v[126:129]
	v_mfma_f32_16x16x32_bf16 v[122:125], v[148:151], v[198:201], v[122:125]
	v_mfma_f32_16x16x32_bf16 v[110:113], v[130:133], v[206:209], v[110:113]
	v_mfma_f32_16x16x32_bf16 v[106:109], v[148:151], v[206:209], v[106:109]
	v_mfma_f32_16x16x32_bf16 v[94:97], v[130:133], v[214:217], v[94:97]
	v_mfma_f32_16x16x32_bf16 v[90:93], v[148:151], v[214:217], v[90:93]
	v_mfma_f32_16x16x32_bf16 v[78:81], v[130:133], v[222:225], v[78:81]
	v_mfma_f32_16x16x32_bf16 v[74:77], v[148:151], v[222:225], v[74:77]
	v_mfma_f32_16x16x32_bf16 v[126:129], v[134:137], v[202:205], v[126:129]
	v_mfma_f32_16x16x32_bf16 v[122:125], v[164:167], v[202:205], v[122:125]
	v_mfma_f32_16x16x32_bf16 v[110:113], v[134:137], v[210:213], v[110:113]
	v_mfma_f32_16x16x32_bf16 v[106:109], v[164:167], v[210:213], v[106:109]
	v_mfma_f32_16x16x32_bf16 v[94:97], v[134:137], v[218:221], v[94:97]
	v_mfma_f32_16x16x32_bf16 v[90:93], v[164:167], v[218:221], v[90:93]
	v_mfma_f32_16x16x32_bf16 v[78:81], v[134:137], v[226:229], v[78:81]
	v_mfma_f32_16x16x32_bf16 v[74:77], v[164:167], v[226:229], v[74:77]
	s_setprio 0
	s_setprio 1
	v_mfma_f32_16x16x32_bf16 v[118:121], v[172:175], v[198:201], v[118:121]
	v_mfma_f32_16x16x32_bf16 v[114:117], v[190:193], v[198:201], v[114:117]
	v_mfma_f32_16x16x32_bf16 v[102:105], v[172:175], v[206:209], v[102:105]
	v_mfma_f32_16x16x32_bf16 v[98:101], v[190:193], v[206:209], v[98:101]
	v_mfma_f32_16x16x32_bf16 v[86:89], v[172:175], v[214:217], v[86:89]
	v_mfma_f32_16x16x32_bf16 v[82:85], v[190:193], v[214:217], v[82:85]
	v_mfma_f32_16x16x32_bf16 v[70:73], v[172:175], v[222:225], v[70:73]
	v_mfma_f32_16x16x32_bf16 v[66:69], v[190:193], v[222:225], v[66:69]
	v_mfma_f32_16x16x32_bf16 v[118:121], v[176:179], v[202:205], v[118:121]
	v_mfma_f32_16x16x32_bf16 v[114:117], v[194:197], v[202:205], v[114:117]
	v_mfma_f32_16x16x32_bf16 v[102:105], v[176:179], v[210:213], v[102:105]
	v_mfma_f32_16x16x32_bf16 v[98:101], v[194:197], v[210:213], v[98:101]
	v_mfma_f32_16x16x32_bf16 v[86:89], v[176:179], v[218:221], v[86:89]
	v_mfma_f32_16x16x32_bf16 v[82:85], v[194:197], v[218:221], v[82:85]
	v_mfma_f32_16x16x32_bf16 v[70:73], v[176:179], v[226:229], v[70:73]
	v_mfma_f32_16x16x32_bf16 v[66:69], v[194:197], v[226:229], v[66:69]
	s_setprio 0
	s_barrier
	s_add_i32 s69, s69, s43
	s_mov_b32 m0, s69
	ds_read_b128 v[198:201], v157 offset:16384
	ds_read_b128 v[202:205], v157 offset:17408
	ds_read_b128 v[206:209], v157 offset:18432
	ds_read_b128 v[210:213], v157 offset:19456
	ds_read_b128 v[214:217], v157 offset:20480
	ds_read_b128 v[218:221], v157 offset:21504
	ds_read_b128 v[222:225], v157 offset:22528
	ds_read_b128 v[226:229], v157 offset:23552
	global_load_lds_dwordx4 v140, s[70:71]
	s_add_i32 m0, s69, 0x2000
	s_add_i32 s69, s72, s43
	global_load_lds_dwordx4 v247, s[70:71]
	s_mov_b32 m0, s69
	s_nop 0
	global_load_lds_dwordx4 v248, s[70:71]
	s_add_i32 m0, s69, 0x2000
	s_nop 0
	global_load_lds_dwordx4 v249, s[70:71]
	s_mov_b64 s[100:101], s[40:41]
	s_mov_b32 m0, s54
	s_nop 0
	global_load_lds_dwordx4 v138, s[100:101]
	s_mov_b32 m0, s55
	s_nop 0
	global_load_lds_dwordx4 v250, s[100:101]
	s_waitcnt vmcnt(8)
	s_waitcnt lgkmcnt(0)
	s_barrier
	s_setprio 1
	s_waitcnt lgkmcnt(0)
	v_mfma_f32_16x16x32_bf16 v[62:65], v[130:133], v[198:201], v[62:65]
	v_mfma_f32_16x16x32_bf16 v[58:61], v[148:151], v[198:201], v[58:61]
	v_mfma_f32_16x16x32_bf16 v[46:49], v[130:133], v[206:209], v[46:49]
	v_mfma_f32_16x16x32_bf16 v[42:45], v[148:151], v[206:209], v[42:45]
	v_mfma_f32_16x16x32_bf16 v[30:33], v[130:133], v[214:217], v[30:33]
	v_mfma_f32_16x16x32_bf16 v[26:29], v[148:151], v[214:217], v[26:29]
	v_mfma_f32_16x16x32_bf16 v[14:17], v[130:133], v[222:225], v[14:17]
	v_mfma_f32_16x16x32_bf16 v[10:13], v[148:151], v[222:225], v[10:13]
	v_mfma_f32_16x16x32_bf16 v[62:65], v[134:137], v[202:205], v[62:65]
	v_mfma_f32_16x16x32_bf16 v[58:61], v[164:167], v[202:205], v[58:61]
	v_mfma_f32_16x16x32_bf16 v[46:49], v[134:137], v[210:213], v[46:49]
	v_mfma_f32_16x16x32_bf16 v[42:45], v[164:167], v[210:213], v[42:45]
	v_mfma_f32_16x16x32_bf16 v[30:33], v[134:137], v[218:221], v[30:33]
	v_mfma_f32_16x16x32_bf16 v[26:29], v[164:167], v[218:221], v[26:29]
	v_mfma_f32_16x16x32_bf16 v[14:17], v[134:137], v[226:229], v[14:17]
	v_mfma_f32_16x16x32_bf16 v[10:13], v[164:167], v[226:229], v[10:13]
	s_setprio 0
	s_setprio 1
	v_mfma_f32_16x16x32_bf16 v[54:57], v[172:175], v[198:201], v[54:57]
	v_mfma_f32_16x16x32_bf16 v[50:53], v[190:193], v[198:201], v[50:53]
	v_mfma_f32_16x16x32_bf16 v[38:41], v[172:175], v[206:209], v[38:41]
	v_mfma_f32_16x16x32_bf16 v[34:37], v[190:193], v[206:209], v[34:37]
	v_mfma_f32_16x16x32_bf16 v[22:25], v[172:175], v[214:217], v[22:25]
	v_mfma_f32_16x16x32_bf16 v[18:21], v[190:193], v[214:217], v[18:21]
	v_mfma_f32_16x16x32_bf16 v[6:9], v[172:175], v[222:225], v[6:9]
	v_mfma_f32_16x16x32_bf16 v[2:5], v[190:193], v[222:225], v[2:5]
	v_mfma_f32_16x16x32_bf16 v[54:57], v[176:179], v[202:205], v[54:57]
	v_mfma_f32_16x16x32_bf16 v[50:53], v[194:197], v[202:205], v[50:53]
	v_mfma_f32_16x16x32_bf16 v[38:41], v[176:179], v[210:213], v[38:41]
	v_mfma_f32_16x16x32_bf16 v[34:37], v[194:197], v[210:213], v[34:37]
	v_mfma_f32_16x16x32_bf16 v[22:25], v[176:179], v[218:221], v[22:25]
	v_mfma_f32_16x16x32_bf16 v[18:21], v[194:197], v[218:221], v[18:21]
	v_mfma_f32_16x16x32_bf16 v[6:9], v[176:179], v[226:229], v[6:9]
	v_mfma_f32_16x16x32_bf16 v[2:5], v[194:197], v[226:229], v[2:5]
	s_setprio 0
	s_barrier
	s_add_i32 s40, 0, 0x18000
	v_add_u32_e32 v145, s40, v155
	s_add_i32 s41, 0, 0x1c000
	ds_read_b128 v[130:133], v145
	ds_read_b128 v[134:137], v145 offset:1024
	ds_read_b128 v[148:151], v145 offset:2048
	ds_read_b128 v[164:167], v145 offset:3072
	v_add_u32_e32 v145, s41, v155
	ds_read_b128 v[172:175], v145
	ds_read_b128 v[176:179], v145 offset:1024
	ds_read_b128 v[190:193], v145 offset:2048
	ds_read_b128 v[194:197], v145 offset:3072
	s_mov_b32 m0, s57
	ds_read_b128 v[198:201], v157 offset:32768
	ds_read_b128 v[202:205], v157 offset:33792
	ds_read_b128 v[206:209], v157 offset:34816
	ds_read_b128 v[210:213], v157 offset:35840
	ds_read_b128 v[214:217], v157 offset:36864
	ds_read_b128 v[218:221], v157 offset:37888
	ds_read_b128 v[222:225], v157 offset:38912
	ds_read_b128 v[226:229], v157 offset:39936
	global_load_lds_dwordx4 v251, s[100:101]
	s_mov_b32 m0, s58
	s_nop 0
	global_load_lds_dwordx4 v232, s[100:101]
	s_waitcnt vmcnt(8)
	s_waitcnt lgkmcnt(0)
	s_barrier
	s_setprio 1
	s_waitcnt lgkmcnt(0)
	v_mfma_f32_16x16x32_bf16 v[126:129], v[130:133], v[198:201], v[126:129]
	v_mfma_f32_16x16x32_bf16 v[122:125], v[148:151], v[198:201], v[122:125]
	v_mfma_f32_16x16x32_bf16 v[110:113], v[130:133], v[206:209], v[110:113]
	v_mfma_f32_16x16x32_bf16 v[106:109], v[148:151], v[206:209], v[106:109]
	v_mfma_f32_16x16x32_bf16 v[94:97], v[130:133], v[214:217], v[94:97]
	v_mfma_f32_16x16x32_bf16 v[90:93], v[148:151], v[214:217], v[90:93]
	v_mfma_f32_16x16x32_bf16 v[78:81], v[130:133], v[222:225], v[78:81]
	v_mfma_f32_16x16x32_bf16 v[74:77], v[148:151], v[222:225], v[74:77]
	v_mfma_f32_16x16x32_bf16 v[126:129], v[134:137], v[202:205], v[126:129]
	v_mfma_f32_16x16x32_bf16 v[122:125], v[164:167], v[202:205], v[122:125]
	v_mfma_f32_16x16x32_bf16 v[110:113], v[134:137], v[210:213], v[110:113]
	v_mfma_f32_16x16x32_bf16 v[106:109], v[164:167], v[210:213], v[106:109]
	v_mfma_f32_16x16x32_bf16 v[94:97], v[134:137], v[218:221], v[94:97]
	v_mfma_f32_16x16x32_bf16 v[90:93], v[164:167], v[218:221], v[90:93]
	v_mfma_f32_16x16x32_bf16 v[78:81], v[134:137], v[226:229], v[78:81]
	v_mfma_f32_16x16x32_bf16 v[74:77], v[164:167], v[226:229], v[74:77]
	s_setprio 0
	s_setprio 1
	v_mfma_f32_16x16x32_bf16 v[118:121], v[172:175], v[198:201], v[118:121]
	v_mfma_f32_16x16x32_bf16 v[114:117], v[190:193], v[198:201], v[114:117]
	v_mfma_f32_16x16x32_bf16 v[102:105], v[172:175], v[206:209], v[102:105]
	v_mfma_f32_16x16x32_bf16 v[98:101], v[190:193], v[206:209], v[98:101]
	v_mfma_f32_16x16x32_bf16 v[86:89], v[172:175], v[214:217], v[86:89]
	v_mfma_f32_16x16x32_bf16 v[82:85], v[190:193], v[214:217], v[82:85]
	v_mfma_f32_16x16x32_bf16 v[70:73], v[172:175], v[222:225], v[70:73]
	v_mfma_f32_16x16x32_bf16 v[66:69], v[190:193], v[222:225], v[66:69]
	v_mfma_f32_16x16x32_bf16 v[118:121], v[176:179], v[202:205], v[118:121]
	v_mfma_f32_16x16x32_bf16 v[114:117], v[194:197], v[202:205], v[114:117]
	v_mfma_f32_16x16x32_bf16 v[102:105], v[176:179], v[210:213], v[102:105]
	v_mfma_f32_16x16x32_bf16 v[98:101], v[194:197], v[210:213], v[98:101]
	v_mfma_f32_16x16x32_bf16 v[86:89], v[176:179], v[218:221], v[86:89]
	v_mfma_f32_16x16x32_bf16 v[82:85], v[194:197], v[218:221], v[82:85]
	v_mfma_f32_16x16x32_bf16 v[70:73], v[176:179], v[226:229], v[70:73]
	v_mfma_f32_16x16x32_bf16 v[66:69], v[194:197], v[226:229], v[66:69]
	s_setprio 0
	s_barrier
	s_add_i32 s40, s40, s43
	s_mov_b32 m0, s40
	ds_read_b128 v[198:201], v157 offset:49152
	ds_read_b128 v[202:205], v157 offset:50176
	ds_read_b128 v[206:209], v157 offset:51200
	ds_read_b128 v[210:213], v157 offset:52224
	ds_read_b128 v[214:217], v157 offset:53248
	ds_read_b128 v[218:221], v157 offset:54272
	ds_read_b128 v[222:225], v157 offset:55296
	ds_read_b128 v[226:229], v157 offset:56320
	global_load_lds_dwordx4 v233, s[70:71]
	s_add_i32 m0, s40, 0x2000
	s_add_i32 s40, s41, s43
	global_load_lds_dwordx4 v234, s[70:71]
	s_mov_b32 m0, s40
	s_nop 0
	global_load_lds_dwordx4 v235, s[70:71]
	s_add_i32 m0, s40, 0x2000
	s_nop 0
	global_load_lds_dwordx4 v236, s[70:71]
	s_mov_b32 m0, s59
	s_nop 0
	global_load_lds_dwordx4 v237, s[100:101]
	s_mov_b32 m0, s60
	s_nop 0
	global_load_lds_dwordx4 v238, s[100:101]
	s_waitcnt vmcnt(8)
	s_waitcnt lgkmcnt(0)
	s_barrier
	s_setprio 1
	s_waitcnt lgkmcnt(0)
	v_mfma_f32_16x16x32_bf16 v[62:65], v[130:133], v[198:201], v[62:65]
	v_mfma_f32_16x16x32_bf16 v[58:61], v[148:151], v[198:201], v[58:61]
	v_mfma_f32_16x16x32_bf16 v[46:49], v[130:133], v[206:209], v[46:49]
	v_mfma_f32_16x16x32_bf16 v[42:45], v[148:151], v[206:209], v[42:45]
	v_mfma_f32_16x16x32_bf16 v[30:33], v[130:133], v[214:217], v[30:33]
	v_mfma_f32_16x16x32_bf16 v[26:29], v[148:151], v[214:217], v[26:29]
	v_mfma_f32_16x16x32_bf16 v[14:17], v[130:133], v[222:225], v[14:17]
	v_mfma_f32_16x16x32_bf16 v[10:13], v[148:151], v[222:225], v[10:13]
	v_mfma_f32_16x16x32_bf16 v[62:65], v[134:137], v[202:205], v[62:65]
	v_mfma_f32_16x16x32_bf16 v[58:61], v[164:167], v[202:205], v[58:61]
	v_mfma_f32_16x16x32_bf16 v[46:49], v[134:137], v[210:213], v[46:49]
	v_mfma_f32_16x16x32_bf16 v[42:45], v[164:167], v[210:213], v[42:45]
	v_mfma_f32_16x16x32_bf16 v[30:33], v[134:137], v[218:221], v[30:33]
	v_mfma_f32_16x16x32_bf16 v[26:29], v[164:167], v[218:221], v[26:29]
	v_mfma_f32_16x16x32_bf16 v[14:17], v[134:137], v[226:229], v[14:17]
	v_mfma_f32_16x16x32_bf16 v[10:13], v[164:167], v[226:229], v[10:13]
	s_setprio 0
	s_setprio 1
	v_mfma_f32_16x16x32_bf16 v[54:57], v[172:175], v[198:201], v[54:57]
	v_mfma_f32_16x16x32_bf16 v[50:53], v[190:193], v[198:201], v[50:53]
	v_mfma_f32_16x16x32_bf16 v[38:41], v[172:175], v[206:209], v[38:41]
	v_mfma_f32_16x16x32_bf16 v[34:37], v[190:193], v[206:209], v[34:37]
	v_mfma_f32_16x16x32_bf16 v[22:25], v[172:175], v[214:217], v[22:25]
	v_mfma_f32_16x16x32_bf16 v[18:21], v[190:193], v[214:217], v[18:21]
	v_mfma_f32_16x16x32_bf16 v[6:9], v[172:175], v[222:225], v[6:9]
	v_mfma_f32_16x16x32_bf16 v[2:5], v[190:193], v[222:225], v[2:5]
	v_mfma_f32_16x16x32_bf16 v[54:57], v[176:179], v[202:205], v[54:57]
	v_mfma_f32_16x16x32_bf16 v[50:53], v[194:197], v[202:205], v[50:53]
	v_mfma_f32_16x16x32_bf16 v[38:41], v[176:179], v[210:213], v[38:41]
	v_mfma_f32_16x16x32_bf16 v[34:37], v[194:197], v[210:213], v[34:37]
	v_mfma_f32_16x16x32_bf16 v[22:25], v[176:179], v[218:221], v[22:25]
	v_mfma_f32_16x16x32_bf16 v[18:21], v[194:197], v[218:221], v[18:21]
	v_mfma_f32_16x16x32_bf16 v[6:9], v[176:179], v[226:229], v[6:9]
	v_mfma_f32_16x16x32_bf16 v[2:5], v[194:197], v[226:229], v[2:5]
	s_setprio 0
	s_barrier
	s_add_i32 s68, s68, 2
	s_add_u32 s38, s38, 0x100
	s_addc_u32 s39, s39, 0
	s_add_u32 s66, s66, 0x100
	s_addc_u32 s67, s67, 0
	s_cmp_gt_u32 s68, 61
	s_cbranch_scc0 .LBB0_3117
	s_and_b64 vcc, exec, s[12:13]
	s_cbranch_vccz .LBB0_3120
	s_barrier
